# EpiProj stores lane-transposed via ds_bpermute so adjacent lanes write contiguous 64B (coalesced)
# speedup vs baseline: 1.0093x; 1.0093x over previous
.LBB0_492:
	v_lshrrev_b32_e32 v160, 2, v213
	v_and_b32_e32 v161, 3, v213
	v_lshlrev_b32_e32 v162, 6, v161
	v_lshl_add_u32 v162, v160, 2, v162
	s_lshl_b32 s4, s65, 8
	v_mov_b32_e32 v140, v145
	v_mov_b32_e32 v141, v144
	s_add_i32 s4, s4, s47
	s_andn2_b64 vcc, exec, s[40:41]
	v_add_u32_e32 v149, s4, v160
	s_lshl_b32 s4, s53, 8
	s_or_b32 s4, s4, s48
	v_lshl_add_u32 v142, v161, 3, s4
	s_lshl_b32 s4, s58, 10
	s_add_i32 s4, s51, s4
	v_lshl_add_u32 v154, v141, 2, s4
	ds_read_b32 v148, v154
	v_ashrrev_i32_e32 v143, 31, v142
	v_mov_b64_e32 v[140:141], s[16:17]
	v_mad_i64_i32 v[150:151], s[4:5], v149, s11, v[140:141]
	v_lshlrev_b64 v[142:143], 1, v[142:143]
	s_waitcnt lgkmcnt(0)
	v_pk_mul_f32 v[128:129], v[128:129], v[148:149] op_sel_hi:[1,0]
	v_pk_mul_f32 v[126:127], v[126:127], v[148:149] op_sel_hi:[1,0]
	v_pk_mul_f32 v[152:153], v[124:125], v[148:149] op_sel_hi:[1,0]
	v_pk_mul_f32 v[124:125], v[122:123], v[148:149] op_sel_hi:[1,0]
	v_lshl_add_u64 v[150:151], v[150:151], 0, v[142:143]
	v_cvt_pk_bf16_f32 v122, v126, v127
	v_cvt_pk_bf16_f32 v123, v128, v129
	v_cvt_pk_bf16_f32 v124, v124, v125
	v_cvt_pk_bf16_f32 v125, v152, v153
	ds_bpermute_b32 v122, v162, v122
	ds_bpermute_b32 v123, v162, v123
	ds_bpermute_b32 v124, v162, v124
	ds_bpermute_b32 v125, v162, v125
	s_waitcnt lgkmcnt(0)
	global_store_dwordx4 v[150:151], v[122:125], off
	v_pk_mul_f32 v[116:117], v[116:117], v[148:149] op_sel_hi:[1,0]
	v_pk_mul_f32 v[114:115], v[114:115], v[148:149] op_sel_hi:[1,0]
	v_pk_mul_f32 v[122:123], v[108:109], v[148:149] op_sel_hi:[1,0]
	v_pk_mul_f32 v[108:109], v[106:107], v[148:149] op_sel_hi:[1,0]
	v_cvt_pk_bf16_f32 v106, v114, v115
	v_cvt_pk_bf16_f32 v107, v116, v117
	v_cvt_pk_bf16_f32 v108, v108, v109
	v_cvt_pk_bf16_f32 v109, v122, v123
	ds_bpermute_b32 v106, v162, v106
	ds_bpermute_b32 v107, v162, v107
	ds_bpermute_b32 v108, v162, v108
	ds_bpermute_b32 v109, v162, v109
	s_waitcnt lgkmcnt(0)
	global_store_dwordx4 v[150:151], v[106:109], off offset:256
	ds_read_b32 v114, v154 offset:64
	s_mov_b64 s[30:31], -1
	v_add_u32_e32 v106, 16, v149
	v_mad_i64_i32 v[106:107], s[4:5], v106, s11, v[140:141]
	v_lshl_add_u64 v[116:117], v[106:107], 0, v[142:143]
	s_waitcnt lgkmcnt(0)
	v_pk_mul_f32 v[108:109], v[120:121], v[114:115] op_sel_hi:[1,0]
	v_pk_mul_f32 v[106:107], v[118:119], v[114:115] op_sel_hi:[1,0]
	v_pk_mul_f32 v[112:113], v[112:113], v[114:115] op_sel_hi:[1,0]
	v_pk_mul_f32 v[110:111], v[110:111], v[114:115] op_sel_hi:[1,0]
	v_cvt_pk_bf16_f32 v106, v106, v107
	v_cvt_pk_bf16_f32 v107, v108, v109
	v_cvt_pk_bf16_f32 v108, v110, v111
	v_cvt_pk_bf16_f32 v109, v112, v113
	ds_bpermute_b32 v106, v162, v106
	ds_bpermute_b32 v107, v162, v107
	ds_bpermute_b32 v108, v162, v108
	ds_bpermute_b32 v109, v162, v109
	s_waitcnt lgkmcnt(0)
	global_store_dwordx4 v[116:117], v[106:109], off
	v_pk_mul_f32 v[100:101], v[100:101], v[114:115] op_sel_hi:[1,0]
	v_pk_mul_f32 v[98:99], v[98:99], v[114:115] op_sel_hi:[1,0]
	v_pk_mul_f32 v[106:107], v[92:93], v[114:115] op_sel_hi:[1,0]
	v_pk_mul_f32 v[92:93], v[90:91], v[114:115] op_sel_hi:[1,0]
	v_cvt_pk_bf16_f32 v90, v98, v99
	v_cvt_pk_bf16_f32 v91, v100, v101
	v_cvt_pk_bf16_f32 v92, v92, v93
	v_cvt_pk_bf16_f32 v93, v106, v107
	ds_bpermute_b32 v90, v162, v90
	ds_bpermute_b32 v91, v162, v91
	ds_bpermute_b32 v92, v162, v92
	ds_bpermute_b32 v93, v162, v93
	s_waitcnt lgkmcnt(0)
	global_store_dwordx4 v[116:117], v[90:93], off offset:256
	ds_read_b32 v98, v154 offset:128
	s_waitcnt lgkmcnt(0)
	v_pk_mul_f32 v[96:97], v[96:97], v[98:99] op_sel_hi:[1,0]
	v_add_u32_e32 v90, 32, v149
	v_mad_i64_i32 v[90:91], s[4:5], v90, s11, v[140:141]
	v_lshl_add_u64 v[100:101], v[90:91], 0, v[142:143]
	v_pk_mul_f32 v[92:93], v[104:105], v[98:99] op_sel_hi:[1,0]
	v_pk_mul_f32 v[90:91], v[102:103], v[98:99] op_sel_hi:[1,0]
	v_pk_mul_f32 v[94:95], v[94:95], v[98:99] op_sel_hi:[1,0]
	v_cvt_pk_bf16_f32 v90, v90, v91
	v_cvt_pk_bf16_f32 v91, v92, v93
	v_cvt_pk_bf16_f32 v92, v94, v95
	v_cvt_pk_bf16_f32 v93, v96, v97
	ds_bpermute_b32 v90, v162, v90
	ds_bpermute_b32 v91, v162, v91
	ds_bpermute_b32 v92, v162, v92
	ds_bpermute_b32 v93, v162, v93
	s_waitcnt lgkmcnt(0)
	global_store_dwordx4 v[100:101], v[90:93], off
	v_pk_mul_f32 v[84:85], v[84:85], v[98:99] op_sel_hi:[1,0]
	v_pk_mul_f32 v[82:83], v[82:83], v[98:99] op_sel_hi:[1,0]
	v_pk_mul_f32 v[90:91], v[76:77], v[98:99] op_sel_hi:[1,0]
	v_pk_mul_f32 v[76:77], v[74:75], v[98:99] op_sel_hi:[1,0]
	v_cvt_pk_bf16_f32 v74, v82, v83
	v_cvt_pk_bf16_f32 v75, v84, v85
	v_cvt_pk_bf16_f32 v76, v76, v77
	v_cvt_pk_bf16_f32 v77, v90, v91
	ds_bpermute_b32 v74, v162, v74
	ds_bpermute_b32 v75, v162, v75
	ds_bpermute_b32 v76, v162, v76
	ds_bpermute_b32 v77, v162, v77
	s_waitcnt lgkmcnt(0)
	global_store_dwordx4 v[100:101], v[74:77], off offset:256
	ds_read_b32 v82, v154 offset:192
	s_waitcnt lgkmcnt(0)
	v_pk_mul_f32 v[80:81], v[80:81], v[82:83] op_sel_hi:[1,0]
	v_add_u32_e32 v74, 48, v149
	v_mad_i64_i32 v[74:75], s[4:5], v74, s11, v[140:141]
	v_lshl_add_u64 v[84:85], v[74:75], 0, v[142:143]
	v_pk_mul_f32 v[76:77], v[88:89], v[82:83] op_sel_hi:[1,0]
	v_pk_mul_f32 v[74:75], v[86:87], v[82:83] op_sel_hi:[1,0]
	v_pk_mul_f32 v[78:79], v[78:79], v[82:83] op_sel_hi:[1,0]
	v_cvt_pk_bf16_f32 v74, v74, v75
	v_cvt_pk_bf16_f32 v75, v76, v77
	v_cvt_pk_bf16_f32 v76, v78, v79
	v_cvt_pk_bf16_f32 v77, v80, v81
	ds_bpermute_b32 v74, v162, v74
	ds_bpermute_b32 v75, v162, v75
	ds_bpermute_b32 v76, v162, v76
	ds_bpermute_b32 v77, v162, v77
	s_waitcnt lgkmcnt(0)
	global_store_dwordx4 v[84:85], v[74:77], off
	v_pk_mul_f32 v[72:73], v[72:73], v[82:83] op_sel_hi:[1,0]
	v_pk_mul_f32 v[70:71], v[70:71], v[82:83] op_sel_hi:[1,0]
	v_pk_mul_f32 v[74:75], v[68:69], v[82:83] op_sel_hi:[1,0]
	v_pk_mul_f32 v[68:69], v[66:67], v[82:83] op_sel_hi:[1,0]
	v_cvt_pk_bf16_f32 v66, v70, v71
	v_cvt_pk_bf16_f32 v67, v72, v73
	v_cvt_pk_bf16_f32 v68, v68, v69
	v_cvt_pk_bf16_f32 v69, v74, v75
	ds_bpermute_b32 v66, v162, v66
	ds_bpermute_b32 v67, v162, v67
	ds_bpermute_b32 v68, v162, v68
	ds_bpermute_b32 v69, v162, v69
	s_waitcnt lgkmcnt(0)
	global_store_dwordx4 v[84:85], v[66:69], off offset:256
	ds_read_b32 v66, v154 offset:512
	s_nop 0
	v_add_u32_e32 v67, 0x80, v149
	v_mad_i64_i32 v[68:69], s[4:5], v67, s11, v[140:141]
	s_waitcnt lgkmcnt(0)
	v_pk_mul_f32 v[64:65], v[64:65], v[66:67] op_sel_hi:[1,0]
	v_pk_mul_f32 v[62:63], v[62:63], v[66:67] op_sel_hi:[1,0]
	v_pk_mul_f32 v[70:71], v[60:61], v[66:67] op_sel_hi:[1,0]
	v_pk_mul_f32 v[60:61], v[58:59], v[66:67] op_sel_hi:[1,0]
	v_lshl_add_u64 v[68:69], v[68:69], 0, v[142:143]
	v_cvt_pk_bf16_f32 v58, v62, v63
	v_cvt_pk_bf16_f32 v59, v64, v65
	v_cvt_pk_bf16_f32 v60, v60, v61
	v_cvt_pk_bf16_f32 v61, v70, v71
	ds_bpermute_b32 v58, v162, v58
	ds_bpermute_b32 v59, v162, v59
	ds_bpermute_b32 v60, v162, v60
	ds_bpermute_b32 v61, v162, v61
	s_waitcnt lgkmcnt(0)
	global_store_dwordx4 v[68:69], v[58:61], off
	v_pk_mul_f32 v[52:53], v[52:53], v[66:67] op_sel_hi:[1,0]
	v_pk_mul_f32 v[50:51], v[50:51], v[66:67] op_sel_hi:[1,0]
	v_pk_mul_f32 v[58:59], v[44:45], v[66:67] op_sel_hi:[1,0]
	v_pk_mul_f32 v[44:45], v[42:43], v[66:67] op_sel_hi:[1,0]
	v_cvt_pk_bf16_f32 v42, v50, v51
	v_cvt_pk_bf16_f32 v43, v52, v53
	v_cvt_pk_bf16_f32 v44, v44, v45
	v_cvt_pk_bf16_f32 v45, v58, v59
	ds_bpermute_b32 v42, v162, v42
	ds_bpermute_b32 v43, v162, v43
	ds_bpermute_b32 v44, v162, v44
	ds_bpermute_b32 v45, v162, v45
	s_waitcnt lgkmcnt(0)
	global_store_dwordx4 v[68:69], v[42:45], off offset:256
	ds_read_b32 v50, v154 offset:576
	s_waitcnt lgkmcnt(0)
	v_pk_mul_f32 v[48:49], v[48:49], v[50:51] op_sel_hi:[1,0]
	v_add_u32_e32 v42, 0x90, v149
	v_mad_i64_i32 v[42:43], s[4:5], v42, s11, v[140:141]
	v_lshl_add_u64 v[52:53], v[42:43], 0, v[142:143]
	v_pk_mul_f32 v[44:45], v[56:57], v[50:51] op_sel_hi:[1,0]
	v_pk_mul_f32 v[42:43], v[54:55], v[50:51] op_sel_hi:[1,0]
	v_pk_mul_f32 v[46:47], v[46:47], v[50:51] op_sel_hi:[1,0]
	v_cvt_pk_bf16_f32 v42, v42, v43
	v_cvt_pk_bf16_f32 v43, v44, v45
	v_cvt_pk_bf16_f32 v44, v46, v47
	v_cvt_pk_bf16_f32 v45, v48, v49
	ds_bpermute_b32 v42, v162, v42
	ds_bpermute_b32 v43, v162, v43
	ds_bpermute_b32 v44, v162, v44
	ds_bpermute_b32 v45, v162, v45
	s_waitcnt lgkmcnt(0)
	global_store_dwordx4 v[52:53], v[42:45], off
	v_pk_mul_f32 v[36:37], v[36:37], v[50:51] op_sel_hi:[1,0]
	v_pk_mul_f32 v[34:35], v[34:35], v[50:51] op_sel_hi:[1,0]
	v_pk_mul_f32 v[42:43], v[28:29], v[50:51] op_sel_hi:[1,0]
	v_pk_mul_f32 v[28:29], v[26:27], v[50:51] op_sel_hi:[1,0]
	v_cvt_pk_bf16_f32 v26, v34, v35
	v_cvt_pk_bf16_f32 v27, v36, v37
	v_cvt_pk_bf16_f32 v28, v28, v29
	v_cvt_pk_bf16_f32 v29, v42, v43
	ds_bpermute_b32 v26, v162, v26
	ds_bpermute_b32 v27, v162, v27
	ds_bpermute_b32 v28, v162, v28
	ds_bpermute_b32 v29, v162, v29
	s_waitcnt lgkmcnt(0)
	global_store_dwordx4 v[52:53], v[26:29], off offset:256
	ds_read_b32 v34, v154 offset:640
	s_waitcnt lgkmcnt(0)
	v_pk_mul_f32 v[32:33], v[32:33], v[34:35] op_sel_hi:[1,0]
	v_add_u32_e32 v26, 0xa0, v149
	v_mad_i64_i32 v[26:27], s[4:5], v26, s11, v[140:141]
	v_lshl_add_u64 v[36:37], v[26:27], 0, v[142:143]
	v_pk_mul_f32 v[28:29], v[40:41], v[34:35] op_sel_hi:[1,0]
	v_pk_mul_f32 v[26:27], v[38:39], v[34:35] op_sel_hi:[1,0]
	v_pk_mul_f32 v[30:31], v[30:31], v[34:35] op_sel_hi:[1,0]
	v_cvt_pk_bf16_f32 v26, v26, v27
	v_cvt_pk_bf16_f32 v27, v28, v29
	v_cvt_pk_bf16_f32 v28, v30, v31
	v_cvt_pk_bf16_f32 v29, v32, v33
	ds_bpermute_b32 v26, v162, v26
	ds_bpermute_b32 v27, v162, v27
	ds_bpermute_b32 v28, v162, v28
	ds_bpermute_b32 v29, v162, v29
	s_waitcnt lgkmcnt(0)
	global_store_dwordx4 v[36:37], v[26:29], off
	v_pk_mul_f32 v[20:21], v[20:21], v[34:35] op_sel_hi:[1,0]
	v_pk_mul_f32 v[18:19], v[18:19], v[34:35] op_sel_hi:[1,0]
	v_pk_mul_f32 v[26:27], v[12:13], v[34:35] op_sel_hi:[1,0]
	v_pk_mul_f32 v[12:13], v[10:11], v[34:35] op_sel_hi:[1,0]
	v_cvt_pk_bf16_f32 v10, v18, v19
	v_cvt_pk_bf16_f32 v11, v20, v21
	v_cvt_pk_bf16_f32 v12, v12, v13
	v_cvt_pk_bf16_f32 v13, v26, v27
	ds_bpermute_b32 v10, v162, v10
	ds_bpermute_b32 v11, v162, v11
	ds_bpermute_b32 v12, v162, v12
	ds_bpermute_b32 v13, v162, v13
	s_waitcnt lgkmcnt(0)
	global_store_dwordx4 v[36:37], v[10:13], off offset:256
	ds_read_b32 v18, v154 offset:704
	s_waitcnt lgkmcnt(0)
	v_pk_mul_f32 v[16:17], v[16:17], v[18:19] op_sel_hi:[1,0]
	v_add_u32_e32 v10, 0xb0, v149
	v_mad_i64_i32 v[10:11], s[4:5], v10, s11, v[140:141]
	v_lshl_add_u64 v[20:21], v[10:11], 0, v[142:143]
	v_pk_mul_f32 v[12:13], v[24:25], v[18:19] op_sel_hi:[1,0]
	v_pk_mul_f32 v[10:11], v[22:23], v[18:19] op_sel_hi:[1,0]
	v_pk_mul_f32 v[14:15], v[14:15], v[18:19] op_sel_hi:[1,0]
	v_cvt_pk_bf16_f32 v10, v10, v11
	v_cvt_pk_bf16_f32 v11, v12, v13
	v_cvt_pk_bf16_f32 v12, v14, v15
	v_cvt_pk_bf16_f32 v13, v16, v17
	ds_bpermute_b32 v10, v162, v10
	ds_bpermute_b32 v11, v162, v11
	ds_bpermute_b32 v12, v162, v12
	ds_bpermute_b32 v13, v162, v13
	s_waitcnt lgkmcnt(0)
	global_store_dwordx4 v[20:21], v[10:13], off
	v_pk_mul_f32 v[8:9], v[8:9], v[18:19] op_sel_hi:[1,0]
	v_pk_mul_f32 v[6:7], v[6:7], v[18:19] op_sel_hi:[1,0]
	v_pk_mul_f32 v[10:11], v[4:5], v[18:19] op_sel_hi:[1,0]
	v_pk_mul_f32 v[4:5], v[2:3], v[18:19] op_sel_hi:[1,0]
	v_cvt_pk_bf16_f32 v2, v6, v7
	v_cvt_pk_bf16_f32 v3, v8, v9
	v_cvt_pk_bf16_f32 v4, v4, v5
	v_cvt_pk_bf16_f32 v5, v10, v11
	ds_bpermute_b32 v2, v162, v2
	ds_bpermute_b32 v3, v162, v3
	ds_bpermute_b32 v4, v162, v4
	ds_bpermute_b32 v5, v162, v5
	s_waitcnt lgkmcnt(0)
	global_store_dwordx4 v[20:21], v[2:5], off offset:256
	s_cbranch_vccnz .LBB0_485
	s_andn2_b64 vcc, exec, s[14:15]
	s_cbranch_vccnz .LBB0_484
	s_barrier
	s_branch .LBB0_484
